# pool_unit weight fragment loads batched 8 pairs per vmcnt(0) wait (was 32 serialized round trips)
# speedup vs baseline: 1.0192x; 1.0109x over previous
; __device__ __forceinline__ unsigned pkbf(float lo, float hi) { return pg8::cvt_pk_bf16(lo, hi); }
; __device__ __forceinline__ void pool_unit(LAS unsigned char* lds, const float* upool, const float* pw  , const float* pscale, bf16_t* mix, int row0) {
;     ...
;     const int r = lane & 31, h = lane >> 5;
;     bf16x8 bw[4][2];
; #pragma unroll
;     for (int ks = 0; ks < 4; ++ks)
; #pragma unroll
;         for (int nt = 0; nt < 2; ++nt) {
;             const float* wp = pw + (size_t)(g * 64 + 16 * ks + 8 * h) * 64 + 32 * nt + r;
;             u32x4 w; w.x = pkbf(wp[0], wp[64]); w.y = pkbf(wp[128], wp[192]); w.z = pkbf(wp[256], wp[320]); w.w = pkbf(wp[384], wp[448]);
;             bw[ks][nt] = __builtin_bit_cast(bf16x8, w);
;         }
;     const float sc0 = pscale[g * 64 + r], sc1 = pscale[g * 64 + 32 + r];
;     __syncthreads();
.LBB0_723:
	v_cvt_f32_i32_e32 v0, s36
	v_and_b32_e32 v32, 31, v2
	v_lshrrev_b32_e32 v68, 5, v3
	v_lshlrev_b32_e32 v176, 2, v32
	v_rcp_iflag_f32_e32 v0, v0
	v_lshlrev_b32_e32 v3, 11, v68
	s_movk_i32 s0, 0x3000
	v_fma_f32 v0, v6, v0, -v5
	ds_write_b32 v4, v0 offset:32240
	v_lshl_add_u64 v[0:1], s[6:7], 0, v[176:177]
	v_lshl_or_b32 v176, s43, 14, v3
	v_lshl_add_u64 v[0:1], v[0:1], 0, v[176:177]
	global_load_dword v198, v[0:1], off offset:256
	global_load_dword v199, v[0:1], off
	v_lshlrev_b32_e32 v176, 1, v32
	global_load_dword v200, v[0:1], off offset:768
	global_load_dword v201, v[0:1], off offset:512
	global_load_dword v202, v[0:1], off offset:1280
	global_load_dword v203, v[0:1], off offset:1024
	global_load_dword v204, v[0:1], off offset:1792
	global_load_dword v205, v[0:1], off offset:1536
	global_load_dword v206, v[0:1], off offset:384
	global_load_dword v207, v[0:1], off offset:128
	global_load_dword v208, v[0:1], off offset:896
	global_load_dword v209, v[0:1], off offset:640
	global_load_dword v210, v[0:1], off offset:1408
	global_load_dword v211, v[0:1], off offset:1152
	global_load_dword v212, v[0:1], off offset:1920
	global_load_dword v213, v[0:1], off offset:1664
	s_waitcnt vmcnt(0)
	v_cvt_pk_bf16_f32 v4, v199, v198
	v_cvt_pk_bf16_f32 v5, v201, v200
	v_cvt_pk_bf16_f32 v6, v203, v202
	v_cvt_pk_bf16_f32 v7, v205, v204
	v_cvt_pk_bf16_f32 v16, v207, v206
	v_cvt_pk_bf16_f32 v17, v209, v208
	v_cvt_pk_bf16_f32 v18, v211, v210
	v_cvt_pk_bf16_f32 v19, v213, v212
	v_add_co_u32_e32 v8, vcc, s96, v0
	s_nop 1
	v_addc_co_u32_e32 v9, vcc, 0, v1, vcc
	v_add_co_u32_e32 v10, vcc, s48, v0
	global_load_dword v198, v[8:9], off offset:256
	s_nop 0
	v_addc_co_u32_e32 v11, vcc, 0, v1, vcc
	global_load_dword v199, v[10:11], off offset:-4096
	global_load_dword v200, v[8:9], off offset:768
	global_load_dword v201, v[8:9], off offset:512
	v_add_co_u32_e32 v0, vcc, s0, v0
	s_movk_i32 s0, 0x410
	s_nop 0
	v_addc_co_u32_e32 v1, vcc, 0, v1, vcc
	global_load_dword v202, v[8:9], off offset:1280
	global_load_dword v203, v[8:9], off offset:1024
	global_load_dword v204, v[8:9], off offset:1792
	global_load_dword v205, v[8:9], off offset:1536
	global_load_dword v206, v[8:9], off offset:384
	global_load_dword v207, v[8:9], off offset:128
	global_load_dword v208, v[8:9], off offset:896
	global_load_dword v209, v[8:9], off offset:640
	global_load_dword v210, v[8:9], off offset:1408
	global_load_dword v211, v[8:9], off offset:1152
	global_load_dword v212, v[8:9], off offset:1920
	s_nop 0
	global_load_dword v213, v[8:9], off offset:1664
	s_waitcnt vmcnt(0)
	v_cvt_pk_bf16_f32 v36, v199, v198
	v_cvt_pk_bf16_f32 v37, v201, v200
	v_cvt_pk_bf16_f32 v38, v203, v202
	v_cvt_pk_bf16_f32 v39, v205, v204
	v_cvt_pk_bf16_f32 v40, v207, v206
	v_cvt_pk_bf16_f32 v41, v209, v208
	v_cvt_pk_bf16_f32 v42, v211, v210
	v_cvt_pk_bf16_f32 v43, v213, v212
	global_load_dword v198, v[10:11], off offset:256
	global_load_dword v199, v[10:11], off
	global_load_dword v200, v[10:11], off offset:768
	global_load_dword v201, v[10:11], off offset:512
	global_load_dword v202, v[10:11], off offset:1280
	global_load_dword v203, v[10:11], off offset:1024
	global_load_dword v204, v[10:11], off offset:1792
	global_load_dword v205, v[10:11], off offset:1536
	global_load_dword v206, v[10:11], off offset:384
	global_load_dword v207, v[10:11], off offset:128
	global_load_dword v208, v[10:11], off offset:896
	global_load_dword v209, v[10:11], off offset:640
	global_load_dword v210, v[10:11], off offset:1408
	global_load_dword v211, v[10:11], off offset:1152
	global_load_dword v212, v[10:11], off offset:1920
	global_load_dword v213, v[10:11], off offset:1664
	s_waitcnt vmcnt(0)
	v_cvt_pk_bf16_f32 v44, v199, v198
	v_cvt_pk_bf16_f32 v45, v201, v200
	v_cvt_pk_bf16_f32 v46, v203, v202
	v_cvt_pk_bf16_f32 v47, v205, v204
	v_cvt_pk_bf16_f32 v48, v207, v206
	v_cvt_pk_bf16_f32 v49, v209, v208
	v_cvt_pk_bf16_f32 v50, v211, v210
	v_cvt_pk_bf16_f32 v51, v213, v212
	global_load_dword v198, v[0:1], off offset:256
	global_load_dword v199, v[0:1], off
	global_load_dword v200, v[0:1], off offset:768
	global_load_dword v201, v[0:1], off offset:512
	global_load_dword v202, v[0:1], off offset:1280
	global_load_dword v203, v[0:1], off offset:1024
	global_load_dword v204, v[0:1], off offset:1792
	global_load_dword v205, v[0:1], off offset:1536
	global_load_dword v206, v[0:1], off offset:384
	global_load_dword v207, v[0:1], off offset:128
	global_load_dword v208, v[0:1], off offset:896
	global_load_dword v209, v[0:1], off offset:640
	global_load_dword v210, v[0:1], off offset:1408
	global_load_dword v211, v[0:1], off offset:1152
	global_load_dword v212, v[0:1], off offset:1920
	s_nop 0
	global_load_dword v213, v[0:1], off offset:1664
	v_and_b32_e32 v1, 32, v2
	s_waitcnt vmcnt(0)
	v_cvt_pk_bf16_f32 v52, v199, v198
	v_cvt_pk_bf16_f32 v53, v201, v200
	v_cvt_pk_bf16_f32 v54, v203, v202
	v_cvt_pk_bf16_f32 v55, v205, v204
	v_cvt_pk_bf16_f32 v56, v207, v206
	v_cvt_pk_bf16_f32 v57, v209, v208
	v_cvt_pk_bf16_f32 v58, v211, v210
	v_cvt_pk_bf16_f32 v59, v213, v212
	v_or_b32_e32 v0, s27, v32
	v_lshlrev_b32_e32 v0, 2, v0
	global_load_dword v34, v0, s[8:9]
	global_load_dword v35, v0, s[8:9] offset:128
	v_or_b32_e32 v0, s38, v32
	v_mul_lo_u32 v0, v0, s0
	s_lshl_b32 s0, s27, 2
	s_add_i32 s0, s0, 0
	v_add3_u32 v33, s0, v0, v1
	s_waitcnt lgkmcnt(0)
	s_barrier
; #define LAS __attribute__((address_space(3)))
; #define LAS __attribute__((address_space(3)))
; __device__ __forceinline__ unsigned pkbf(float lo, float hi) { return pg8::cvt_pk_bf16(lo, hi); }
; __device__ __forceinline__ void pool_unit(LAS unsigned char* lds, const float* upool, const float* pw  , const float* pscale, bf16_t* mix, int row0) {
;     ...
;     {
;         f32x16 d0, d1;
; #pragma unroll
;         for (int i = 0; i < 16; ++i) { d0[i] = 0.f; d1[i] = 0.f; }
;         const LAS float* pa = P + (half * 32 + r) * PPITCH + g * 64 + 8 * h;
; #pragma unroll
;         for (int ks = 0; ks < 4; ++ks) {
;             const f32x4 a0 = *(const LAS f32x4*)(pa + 16 * ks), a1 = *(const LAS f32x4*)(pa + 16 * ks + 4);
;             u32x4 w; w.x = pkbf(a0[0], a0[1]); w.y = pkbf(a0[2], a0[3]); w.z = pkbf(a1[0], a1[1]); w.w = pkbf(a1[2], a1[3]);
;             const bf16x8 af = __builtin_bit_cast(bf16x8, w);
;             d0 = __builtin_amdgcn_mfma_f32_32x32x16_bf16(af, bw[ks][0], d0, 0, 0, 0);
;             d1 = __builtin_amdgcn_mfma_f32_32x32x16_bf16(af, bw[ks][1], d1, 0, 0, 0);
;         }
;         bf16_t* ob = mix + (size_t)(row0 + half * 32) * DM + 512 + g * 64 + r;
; #pragma unroll
;         for (int i = 0; i < 16; ++i) {
;             const int tk = (i & 3) + 8 * (i >> 2) + 4 * h;
;             const unsigned bits = pkbf(d0[i] * sc0, d1[i] * sc1);
;             ob[(size_t)tk * DM] = (bf16_t)(bits & 0xffffu);
;             ob[(size_t)tk * DM + 32] = (bf16_t)(bits >> 16);
;         }
;     }
;     __syncthreads();
	ds_read_b128 v[0:3], v33
	ds_read_b128 v[8:11], v33 offset:16
	s_waitcnt lgkmcnt(1)
	v_cvt_pk_bf16_f32 v20, v0, v1
	v_cvt_pk_bf16_f32 v21, v2, v3
	s_waitcnt lgkmcnt(0)
	v_cvt_pk_bf16_f32 v22, v8, v9
	v_cvt_pk_bf16_f32 v23, v10, v11
	ds_read_b128 v[60:63], v33 offset:64
	ds_read_b128 v[64:67], v33 offset:80
	v_mfma_f32_32x32x16_bf16 v[0:15], v[20:23], v[4:7], 0
	s_waitcnt lgkmcnt(1)
	v_cvt_pk_bf16_f32 v60, v60, v61
	v_cvt_pk_bf16_f32 v61, v62, v63
	s_waitcnt lgkmcnt(0)
	v_cvt_pk_bf16_f32 v62, v64, v65
	v_cvt_pk_bf16_f32 v63, v66, v67
	s_add_i32 s0, s38, s26
	v_mfma_f32_32x32x16_bf16 v[16:31], v[20:23], v[16:19], 0
	s_ashr_i32 s1, s0, 31
	s_lshl_b64 s[0:1], s[0:1], 11
	s_add_u32 s0, s4, s0
	s_addc_u32 s1, s5, s1
	s_lshl_b32 s14, s27, 1
	s_add_u32 s0, s0, s14
	s_addc_u32 s1, s1, 0
	v_mfma_f32_32x32x16_bf16 v[0:15], v[60:63], v[36:39], v[0:15]
	s_mov_b64 s[14:15], 0
	v_mfma_f32_32x32x16_bf16 v[16:31], v[60:63], v[40:43], v[16:31]
	ds_read_b128 v[36:39], v33 offset:128
	ds_read_b128 v[40:43], v33 offset:144
	s_waitcnt lgkmcnt(1)
	v_cvt_pk_bf16_f32 v36, v36, v37
	v_cvt_pk_bf16_f32 v37, v38, v39
	s_waitcnt lgkmcnt(0)
	v_cvt_pk_bf16_f32 v38, v40, v41
	v_cvt_pk_bf16_f32 v39, v42, v43
	s_nop 0
	v_mfma_f32_32x32x16_bf16 v[0:15], v[36:39], v[44:47], v[0:15]
	v_mfma_f32_32x32x16_bf16 v[16:31], v[36:39], v[48:51], v[16:31]
	ds_read_b128 v[36:39], v33 offset:192
	ds_read_b128 v[40:43], v33 offset:208
	s_waitcnt lgkmcnt(1)
	v_cvt_pk_bf16_f32 v36, v36, v37
	v_cvt_pk_bf16_f32 v37, v38, v39
	s_waitcnt lgkmcnt(0)
	v_cvt_pk_bf16_f32 v38, v40, v41
	v_cvt_pk_bf16_f32 v39, v42, v43
	v_lshl_add_u64 v[32:33], s[0:1], 0, v[176:177]
	v_mfma_f32_32x32x16_bf16 v[0:15], v[36:39], v[52:55], v[0:15]
	v_lshlrev_b32_e32 v176, 13, v68
	v_lshl_add_u64 v[32:33], v[32:33], 0, v[176:177]
	s_mov_b64 s[0:1], 0xe100400
	v_mfma_f32_32x32x16_bf16 v[16:31], v[36:39], v[56:59], v[16:31]
	v_lshl_add_u64 v[36:37], v[32:33], 0, s[0:1]
	s_mov_b32 s0, 0xe100000
	s_waitcnt vmcnt(1)
	s_nop 4
	v_mul_f32_e32 v0, v34, v0
	v_add_co_u32_e32 v38, vcc, s0, v32
	s_mov_b32 s0, 0xe101000
	s_nop 0
	v_addc_co_u32_e32 v39, vcc, 0, v33, vcc
	s_waitcnt vmcnt(0)
	v_mul_f32_e32 v16, v35, v16
	v_cvt_pk_bf16_f32 v0, v0, v16
	flat_store_short v[38:39], v0 offset:1024
	flat_store_short_d16_hi v[36:37], v0 offset:64
	v_mul_f32_e32 v0, v34, v1
	v_mul_f32_e32 v1, v35, v17
	v_cvt_pk_bf16_f32 v0, v0, v1
	flat_store_short v[36:37], v0 offset:2048
	flat_store_short_d16_hi v[36:37], v0 offset:2112
	v_mul_f32_e32 v0, v34, v2
	v_mul_f32_e32 v1, v35, v18
	v_cvt_pk_bf16_f32 v2, v0, v1
	v_add_co_u32_e32 v0, vcc, s0, v32
	s_mov_b32 s0, 0xe104000
	s_nop 0
	v_addc_co_u32_e32 v1, vcc, 0, v33, vcc
	flat_store_short v[0:1], v2 offset:1024
	flat_store_short_d16_hi v[0:1], v2 offset:1088
	v_mul_f32_e32 v2, v34, v3
	v_mul_f32_e32 v3, v35, v19
	v_cvt_pk_bf16_f32 v2, v2, v3
	flat_store_short v[0:1], v2 offset:3072
	flat_store_short_d16_hi v[0:1], v2 offset:3136
	v_mul_f32_e32 v0, v34, v4
	v_mul_f32_e32 v1, v35, v20
	v_cvt_pk_bf16_f32 v2, v0, v1
	v_add_co_u32_e32 v0, vcc, s0, v32
	v_mul_f32_e32 v3, v35, v21
	s_nop 0
	v_addc_co_u32_e32 v1, vcc, 0, v33, vcc
	flat_store_short v[0:1], v2 offset:1024
	flat_store_short_d16_hi v[0:1], v2 offset:1088
	v_mul_f32_e32 v2, v34, v5
	v_cvt_pk_bf16_f32 v2, v2, v3
	flat_store_short v[0:1], v2 offset:3072
	flat_store_short_d16_hi v[0:1], v2 offset:3136
	v_mul_f32_e32 v0, v34, v6
	s_mov_b32 s0, 0xe105000
	v_mul_f32_e32 v1, v35, v22
	v_cvt_pk_bf16_f32 v2, v0, v1
	v_add_co_u32_e32 v0, vcc, s0, v32
	v_mul_f32_e32 v3, v35, v23
	s_nop 0
	v_addc_co_u32_e32 v1, vcc, 0, v33, vcc
	flat_store_short v[0:1], v2 offset:1024
	flat_store_short_d16_hi v[0:1], v2 offset:1088
	v_mul_f32_e32 v2, v34, v7
	v_cvt_pk_bf16_f32 v2, v2, v3
	flat_store_short v[0:1], v2 offset:3072
	flat_store_short_d16_hi v[0:1], v2 offset:3136
	v_mul_f32_e32 v0, v34, v8
	s_mov_b32 s0, 0xe108000
	v_mul_f32_e32 v1, v35, v24
	v_cvt_pk_bf16_f32 v2, v0, v1
	v_add_co_u32_e32 v0, vcc, s0, v32
	v_mul_f32_e32 v3, v35, v25
	s_nop 0
	v_addc_co_u32_e32 v1, vcc, 0, v33, vcc
	flat_store_short v[0:1], v2 offset:1024
	flat_store_short_d16_hi v[0:1], v2 offset:1088
	v_mul_f32_e32 v2, v34, v9
	v_cvt_pk_bf16_f32 v2, v2, v3
	flat_store_short v[0:1], v2 offset:3072
	flat_store_short_d16_hi v[0:1], v2 offset:3136
	v_mul_f32_e32 v0, v34, v10
	s_mov_b32 s0, 0xe109000
	v_mul_f32_e32 v1, v35, v26
	v_cvt_pk_bf16_f32 v2, v0, v1
	v_add_co_u32_e32 v0, vcc, s0, v32
	v_mul_f32_e32 v3, v35, v27
	s_nop 0
	v_addc_co_u32_e32 v1, vcc, 0, v33, vcc
	flat_store_short v[0:1], v2 offset:1024
	flat_store_short_d16_hi v[0:1], v2 offset:1088
	v_mul_f32_e32 v2, v34, v11
	v_cvt_pk_bf16_f32 v2, v2, v3
	flat_store_short v[0:1], v2 offset:3072
	flat_store_short_d16_hi v[0:1], v2 offset:3136
	v_mul_f32_e32 v0, v34, v12
	s_mov_b32 s0, 0xe10c000
	v_mul_f32_e32 v1, v35, v28
	v_cvt_pk_bf16_f32 v2, v0, v1
	v_add_co_u32_e32 v0, vcc, s0, v32
	v_mul_f32_e32 v3, v35, v29
	s_nop 0
	v_addc_co_u32_e32 v1, vcc, 0, v33, vcc
	flat_store_short v[0:1], v2 offset:1024
	flat_store_short_d16_hi v[0:1], v2 offset:1088
	v_mul_f32_e32 v2, v34, v13
	v_cvt_pk_bf16_f32 v2, v2, v3
	flat_store_short v[0:1], v2 offset:3072
	flat_store_short_d16_hi v[0:1], v2 offset:3136
	v_mul_f32_e32 v0, v34, v14
	s_mov_b32 s0, 0xe10d000
	v_mul_f32_e32 v1, v35, v30
	v_cvt_pk_bf16_f32 v2, v0, v1
	v_add_co_u32_e32 v0, vcc, s0, v32
	v_mul_f32_e32 v3, v35, v31
	s_nop 0
	v_addc_co_u32_e32 v1, vcc, 0, v33, vcc
	flat_store_short v[0:1], v2 offset:1024
	flat_store_short_d16_hi v[0:1], v2 offset:1088
	v_mul_f32_e32 v2, v34, v15
	v_cvt_pk_bf16_f32 v2, v2, v3
	flat_store_short v[0:1], v2 offset:3072
	flat_store_short_d16_hi v[0:1], v2 offset:3136
	s_waitcnt lgkmcnt(0)
	s_barrier
